# P2 item prologues (diff and retention): first-tile wait + barrier moved below the register-only set-up (accumulator zeroing, decay factors) so that work runs under the DMA latency
# speedup vs baseline: 1.0142x; 1.0005x over previous
; template <bool DIFF>
; __device__ __forceinline__ void attn_item(LAS unsigned char* lds, const bf16_t* Z, bf16_t* MIX, int b, int h, int t, float lam, float shift, const float* gain, int tid, int wid, int lane) {
;     ...
;     lane = lane_id(); asm volatile("" : "+v"(lane)); tid = wid * 64 + lane;
;     const int q16 = lane & 15, quad = lane >> 4;
;     const int row0 = b * SEQ + 128 * t + 16 * wid;
;     const int cq = 2 * t + (wid >> 2), nkt = 2 * t + 2;
;     const int qcol = DIFF ? (3072 + 128 * h) : (64 * h);
;     const int kcol = DIFF ? (4096 + 128 * h) : (512 + 64 * h);
;     const int vcol = DIFF ? (5120 + 128 * h) : (1024 + 128 * h);
;     const int gcol = DIFF ? (6144 + 128 * h) : (2048 + 128 * h);
;     const float lg = lg2gamma(h);
;     bf16x8 qf[NC][2];
;     { const bf16_t* qrow = Z + (size_t)(row0 + q16) * DIN + qcol;
; #pragma unroll
;       for (int c = 0; c < NC; ++c)
; #pragma unroll
;           for (int ds = 0; ds < 2; ++ds) qf[c][ds] = __builtin_nontemporal_load((const bf16x8*)(qrow + 64 * c + 32 * ds + 8 * quad)); }
;     f32x4 O[NC][8]; float l[NC];
; #pragma unroll
;     for (int c = 0; c < NC; ++c) { l[c] = 0.f;
; #pragma unroll
;         for (int eb = 0; eb < 8; ++eb) O[c][eb] = (f32x4){0.f, 0.f, 0.f, 0.f}; }
;     const char* kbase = (const char*)(Z + (size_t)(b * SEQ) * DIN + kcol);
;     const char* vbase = (const char*)(Z + (size_t)(b * SEQ) * DIN + vcol);
;     const unsigned krow = (unsigned)(8 * wid + (lane >> 3));
;     const unsigned kso = (krow * DIN + 8u * ((unsigned)(lane & 7) ^ (krow & 7u))) * 2u;
;     const unsigned vrow = (unsigned)(4 * wid + (lane >> 4));
;     const unsigned vso = (vrow * DIN + 8u * (2u * ((((unsigned)lane & 15u) >> 1) ^ (vrow & 7u)) + ((unsigned)lane & 1u))) * 2u;
;     constexpr int ATT_RING = 32768;
;     ...
;     asm volatile("s_waitcnt lgkmcnt(0)\n\ts_barrier" ::: "memory");
;     ATT_DMA(0, 0); ATT_DMA(1, 1);
;     ATT_WAITBAR_ONE();
;     const unsigned kfo = (unsigned)(q16 * 128), ksw = (unsigned)(q16 & 7);
;     const unsigned vrr = (unsigned)(4 * quad + (q16 >> 2)), vx32 = (vrr & 7u) * 32u, vb0 = 16384u + vrr * 256u + 8u * (unsigned)(q16 & 3);
;     const float iq = (float)(128 * t + 16 * wid + q16);
;     int bcur = 0;
;     for (int kt = 0; kt < nkt; ++kt) {
;         const int bnx = (bcur == 2) ? 0 : bcur + 1, bn2 = (bnx == 2) ? 0 : bnx + 1;
;         const bool more2 = (kt + 2 < nkt);
.LBB0_565:
	v_writelane_b32 v254, s2, 51
	s_and_b32 s0, s2, 0xfffff800
	s_mul_hi_i32 s6, s0, 0x3800
	s_mul_i32 s7, s0, 0x3800
	v_readlane_b32 s0, v254, 25
	s_add_u32 s0, s0, s7
	v_readlane_b32 s1, v254, 26
	s_addc_u32 s1, s1, s6
	s_bfe_u32 s9, s95, 0x30003
	s_lshl_b32 s26, s9, 8
	s_add_u32 s76, s0, s26
	s_addc_u32 s77, s1, 0
	s_and_b32 s10, s95, 7
	s_lshl_b32 s0, s10, 2
	s_lshr_b32 s0, s99, s0
	s_and_b32 s0, s0, 15
	s_lshl_b32 s1, s95, 5
	s_and_b32 s11, s1, 0xfffff800
	s_lshl_b32 s8, s0, 7
	v_mov_b32_e32 v8, v183
	s_or_b32 s1, s8, s11
	s_add_i32 s45, s1, s29
	v_and_b32_e32 v9, 15, v8
	v_or_b32_e32 v124, s45, v9
	v_mov_b64_e32 v[4:5], s[30:31]
	v_ashrrev_i32_e32 v10, 4, v8
	s_lshl_b32 s70, s0, 1
	v_mad_i64_i32 v[4:5], s[0:1], v124, s36, v[4:5]
	s_add_i32 s83, s70, s66
	s_lshl_b32 s80, s9, 7
	v_lshl_add_u64 v[126:127], v[4:5], 0, s[26:27]
	v_lshlrev_b32_e32 v4, 3, v10
	s_mul_i32 s1, s11, 0x3800
	v_ashrrev_i32_e32 v5, 31, v4
	s_mul_hi_i32 s0, s11, 0x3800
	s_add_u32 s12, s30, s1
	v_lshl_add_u64 v[4:5], v[4:5], 1, v[126:127]
	s_addc_u32 s13, s31, s0
	v_lshl_add_u64 v[6:7], v[4:5], 0, s[14:15]
	v_add_co_u32_e32 v4, vcc, s16, v4
	s_add_u32 s71, s12, s26
	s_nop 0
	v_addc_co_u32_e32 v5, vcc, 0, v5, vcc
	global_load_dwordx4 v[76:79], v[6:7], off offset:64 nt
	global_load_dwordx4 v[72:75], v[6:7], off offset:128 nt
	global_load_dwordx4 v[80:83], v[4:5], off offset:2048 nt
	global_load_dwordx4 v[68:71], v[6:7], off offset:192 nt
	s_addc_u32 s94, s13, 0
	v_ashrrev_i32_e32 v4, 3, v8
	s_add_u32 s0, s71, 0x2000
	v_add_u32_e32 v5, s34, v4
	v_xor_b32_e32 v4, v4, v8
	s_addc_u32 s1, s94, 0
	v_mul_lo_u32 v5, v5, s37
	v_lshlrev_b32_e32 v4, 3, v4
	s_add_u32 s2, s71, 0x2800
	v_and_or_b32 v4, v4, 56, v5
	v_writelane_b32 v254, s0, 52
	s_addc_u32 s3, s94, 0
	v_lshlrev_b32_e32 v180, 1, v4
	v_add_u32_e32 v4, s35, v10
	v_writelane_b32 v254, s1, 53
	v_lshlrev_b32_e32 v5, 1, v4
	v_writelane_b32 v254, s2, 54
	v_xor_b32_e32 v5, v5, v8
	v_and_b32_e32 v6, 1, v8
	s_waitcnt lgkmcnt(0)
	s_barrier
	v_writelane_b32 v254, s3, 55
	s_add_u32 s4, s2, 0x70000
	s_mov_b32 m0, s90
	v_and_or_b32 v6, v5, 14, v6
	v_mul_lo_u32 v7, v4, s36
	s_addc_u32 s5, s3, 0
	v_lshl_add_u64 v[4:5], s[0:1], 0, v[180:181]
	global_load_lds_dwordx4 v180, s[0:1]
	v_lshl_add_u64 v[4:5], v[4:5], 0, s[96:97]
	s_mov_b32 m0, s17
	v_lshl_or_b32 v132, v6, 4, v7
	global_load_lds_dwordx4 v[4:5], off
	s_mov_b32 m0, s43
	s_add_u32 s0, s71, 0xe2000
	global_load_lds_dwordx4 v132, s[2:3]
	s_mov_b32 m0, s38
	s_addc_u32 s1, s94, 0
	global_load_lds_dwordx4 v132, s[4:5]
	v_writelane_b32 v254, s0, 56
	s_add_u32 s4, s71, 0xe2800
	s_addc_u32 s5, s94, 0
	v_writelane_b32 v254, s1, 57
	v_writelane_b32 v254, s4, 58
	s_mov_b32 m0, s39
	v_lshl_add_u64 v[4:5], s[0:1], 0, v[180:181]
	v_writelane_b32 v254, s5, 59
	s_add_u32 s14, s4, 0x70000
	s_addc_u32 s15, s5, 0
	global_load_lds_dwordx4 v180, s[0:1]
	v_lshl_add_u64 v[4:5], v[4:5], 0, s[96:97]
	s_mov_b32 m0, s18
	v_lshlrev_b32_e32 v128, 2, v10
	global_load_lds_dwordx4 v[4:5], off
	s_mov_b32 m0, s40
	v_bfe_u32 v4, v8, 2, 2
	global_load_lds_dwordx4 v132, s[4:5]
	s_mov_b32 m0, s41
	v_lshlrev_b32_e32 v6, 3, v8
	global_load_lds_dwordx4 v132, s[14:15]
	v_or_b32_e32 v4, v128, v4
	v_and_b32_e32 v6, 24, v6
	v_lshlrev_b32_e32 v5, 5, v4
	v_lshl_or_b32 v4, v4, 8, v6
	v_add_u32_e32 v143, 0x4000, v4
	v_bitop3_b32 v4, v10, v8, 7 bitop3:0x78
	v_lshlrev_b32_e32 v145, 4, v4
	v_add_u32_e32 v4, 4, v10
	v_bitop3_b32 v4, v4, v8, 7 bitop3:0x78
	v_mov_b32_e32 v6, v181
	v_mov_b32_e32 v7, v181
	v_lshlrev_b32_e32 v144, 7, v9
	v_and_b32_e32 v142, 0xe0, v5
	v_lshlrev_b32_e32 v146, 4, v4
	v_bitop3_b32 v141, v5, 32, v186 bitop3:0x6c
	v_bitop3_b32 v140, v5, 64, v186 bitop3:0x6c
	v_bitop3_b32 v139, v5, s73, v186 bitop3:0x6c
	v_bitop3_b32 v138, v5, s74, v186 bitop3:0x6c
	v_bitop3_b32 v137, v5, s75, v186 bitop3:0x6c
	v_bitop3_b32 v136, v5, s79, v186 bitop3:0x6c
	v_bitop3_b32 v129, v5, s67, v5 bitop3:0xc
	v_mov_b32_e32 v4, v181
	v_mov_b32_e32 v5, v181
	v_mov_b64_e32 v[14:15], v[6:7]
	v_mov_b64_e32 v[22:23], v[6:7]
	v_mov_b64_e32 v[30:31], v[6:7]
	v_mov_b64_e32 v[38:39], v[6:7]
	v_mov_b64_e32 v[46:47], v[6:7]
	v_mov_b64_e32 v[54:55], v[6:7]
	v_mov_b64_e32 v[58:59], v[6:7]
	v_mov_b64_e32 v[10:11], v[6:7]
	v_mov_b64_e32 v[18:19], v[6:7]
	v_mov_b64_e32 v[26:27], v[6:7]
	v_mov_b64_e32 v[34:35], v[6:7]
	v_mov_b64_e32 v[42:43], v[6:7]
	v_mov_b64_e32 v[50:51], v[6:7]
	v_mov_b64_e32 v[62:63], v[6:7]
	v_mov_b64_e32 v[66:67], v[6:7]
	v_ashrrev_i32_e32 v125, 31, v124
	s_mov_b32 s17, 0
	v_mov_b32_e32 v133, v181
	v_mov_b32_e32 v130, v181
	v_mov_b32_e32 v131, v181
	s_mov_b64 s[4:5], s[76:77]
	v_mov_b64_e32 v[12:13], v[4:5]
	v_mov_b64_e32 v[20:21], v[4:5]
	v_mov_b64_e32 v[28:29], v[4:5]
	v_mov_b64_e32 v[36:37], v[4:5]
	v_mov_b64_e32 v[44:45], v[4:5]
	v_mov_b64_e32 v[52:53], v[4:5]
	v_mov_b64_e32 v[56:57], v[4:5]
	v_mov_b64_e32 v[8:9], v[4:5]
	v_mov_b64_e32 v[16:17], v[4:5]
	v_mov_b64_e32 v[24:25], v[4:5]
	v_mov_b64_e32 v[32:33], v[4:5]
	v_mov_b64_e32 v[40:41], v[4:5]
	v_mov_b64_e32 v[48:49], v[4:5]
	v_mov_b64_e32 v[60:61], v[4:5]
	s_mov_b32 s15, 0
	v_mov_b64_e32 v[64:65], v[4:5]
	s_waitcnt vmcnt(4) lgkmcnt(0)
	s_barrier
	s_mov_b64 s[4:5], s[76:77]
	s_mov_b32 s15, 0
	s_and_b32 s0, s15, 3
	s_lshl_b32 s0, s0, 15
	s_add_i32 s1, s15, 3
	s_and_b32 s1, s1, 3
	s_lshl_b32 s1, s1, 15
	s_add_i32 s16, s15, 2
	s_and_b32 s16, s16, 3
	s_lshl_b32 s16, s16, 15
	s_add_i32 s16, s16, s90
	v_add_u32_e32 v119, s0, v144
	v_add_u32_e32 v116, v119, v145
	v_add_u32_e32 v117, v119, v146
	ds_read_b128 v[84:87], v116
	ds_read_b128 v[88:91], v116 offset:2048
	ds_read_b128 v[92:95], v117
	ds_read_b128 v[96:99], v117 offset:2048
	ds_read_b128 v[100:103], v116 offset:4096
	ds_read_b128 v[104:107], v116 offset:6144
	ds_read_b128 v[108:111], v117 offset:4096
	ds_read_b128 v[112:115], v117 offset:6144
	s_cmp_ge_u32 s15, s70
	s_cbranch_scc1 .Ldx_nd0
	s_add_u32 s18, s4, 0xfffff800
	s_addc_u32 s19, s5, -1
	s_add_u32 s22, s18, 0x80
	s_addc_u32 s23, s19, 0
	s_add_u32 s24, s4, 0x70000
	s_addc_u32 s25, s5, 0
	s_mov_b32 m0, s16
	s_nop 0
	global_load_lds_dwordx4 v180, s[18:19]
	s_add_i32 m0, s16, 0x2000
	s_nop 0
	global_load_lds_dwordx4 v180, s[22:23]
	s_add_i32 m0, s16, 0x4000
	s_nop 0
	global_load_lds_dwordx4 v132, s[4:5]
	s_add_i32 m0, s16, 0x6000
	s_nop 0
	global_load_lds_dwordx4 v132, s[24:25]
	s_add_u32 s4, s4, 0xe0000
	s_addc_u32 s5, s5, 0

; #define LAS __attribute__((address_space(3)))
; __device__ __forceinline__ int lane_id() { return (int)__builtin_amdgcn_mbcnt_hi(~0u, __builtin_amdgcn_mbcnt_lo(~0u, 0u)); }
; __device__ __forceinline__ void ret_pair(LAS unsigned char* lds, const bf16_t* Z, bf16_t* MIX, int b, int h, int tA, int tB, const float* gain, int wid) {
;     int lane = lane_id(); asm volatile("" : "+v"(lane));
;     const int q16 = lane & 15, quad = lane >> 4;
;     const int rowA0 = b * SEQ + 128 * tA + 16 * wid, rowB0 = b * SEQ + 128 * tB + 16 * wid;
;     const int cqA = 2 * tA + (wid >> 2), cqB = 2 * tB + (wid >> 2), nkt = 2 * tA + 2;
;     const int qcol = 64 * h, kcol = 512 + 64 * h, vcol = 1024 + 128 * h, gcol = 2048 + 128 * h;
;     const float lg = lg2gamma(h);
;     bf16x8 qfA[2], qfB[2];
;     { const bf16_t* qa = Z + (size_t)(rowA0 + q16) * DIN + qcol; const bf16_t* qb = Z + (size_t)(rowB0 + q16) * DIN + qcol;
; #pragma unroll
;       for (int ds = 0; ds < 2; ++ds) { qfA[ds] = __builtin_nontemporal_load((const bf16x8*)(qa + 32 * ds + 8 * quad)); qfB[ds] = __builtin_nontemporal_load((const bf16x8*)(qb + 32 * ds + 8 * quad)); } }
;     f32x4 OA[8], OB[8];
; #pragma unroll
;     for (int eb = 0; eb < 8; ++eb) { OA[eb] = (f32x4){0.f, 0.f, 0.f, 0.f}; OB[eb] = OA[eb]; }
;     const char* kbase = (const char*)(Z + (size_t)(b * SEQ) * DIN + kcol);
;     const char* vbase = (const char*)(Z + (size_t)(b * SEQ) * DIN + vcol);
;     const unsigned krow = (unsigned)(8 * wid + (lane >> 3));
;     const unsigned kso = (krow * DIN + 8u * ((unsigned)(lane & 7) ^ (krow & 7u))) * 2u;
;     const unsigned vrow = (unsigned)(4 * wid + (lane >> 4));
;     const unsigned vso = (vrow * DIN + 8u * (2u * ((((unsigned)lane & 15u) >> 1) ^ (vrow & 7u)) + ((unsigned)lane & 1u))) * 2u;
;     constexpr int RING = 32768;
;     ...
;     asm volatile("s_waitcnt lgkmcnt(0)\n\ts_barrier" ::: "memory");
;     RP_DMA(0, 0); RP_DMA(1, 1);
;     asm volatile("s_waitcnt vmcnt(3) lgkmcnt(0)\n\ts_barrier" ::: "memory");
;     const unsigned kfo = (unsigned)(q16 * 128), ksw = (unsigned)(q16 & 7);
;     const unsigned vrr = (unsigned)(4 * quad + (q16 >> 2)), vx32 = (vrr & 7u) * 32u, vb0 = 16384u + vrr * 256u + 8u * (unsigned)(q16 & 3);
;     const float iqA = (float)(128 * tA + 16 * wid + q16), iqB = (float)(128 * tB + 16 * wid + q16);
.LBB0_595:
	s_lshl_b32 s1, s10, 2
	s_lshr_b32 s1, 0x76543210, s1
	s_and_b32 s1, s1, 15
	s_lshl_b32 s14, s1, 8
	s_or_b32 s0, s14, s11
	v_writelane_b32 v255, s95, 1
	s_add_i32 s5, s0, s29
	s_add_i32 s8, s14, 0x80
	s_or_b32 s45, s8, s11
	s_add_i32 s45, s45, s29
	s_lshl_b32 s82, s1, 2
	s_add_i32 s70, s82, 2
	s_add_i32 s83, s70, s66
	s_add_i32 s0, s70, -1
	s_cmp_lt_u32 s0, s83
	s_cselect_b64 s[2:3], -1, 0
	v_writelane_b32 v254, s2, 60
	v_writelane_b32 v254, s3, 61
	v_writelane_b32 v254, s0, 62
	s_cmp_lt_u32 s70, s83
	s_cselect_b64 s[2:3], -1, 0
	v_writelane_b32 v254, s2, 63
	v_writelane_b32 v255, s3, 0
	v_writelane_b32 v255, s44, 2
	s_mov_b32 s0, s82
	s_add_i32 s91, s82, s66
	v_writelane_b32 v255, s0, 3
	s_add_i32 s72, s66, s0
	v_readlane_b32 s0, v254, 28
	s_add_u32 s0, s0, s7
	v_readlane_b32 s1, v254, 29
	s_addc_u32 s1, s1, s6
	s_add_u32 s2, s0, s26
	s_addc_u32 s3, s1, 0
	v_readlane_b32 s0, v254, 30
	s_add_u32 s0, s0, s7
	v_readlane_b32 s1, v254, 31
	v_and_b32_e32 v14, 15, v15
	s_addc_u32 s1, s1, s6
	s_lshl_b32 s4, s9, 7
	s_add_u32 s84, s0, s4
	v_or_b32_e32 v6, s45, v14
	v_mov_b64_e32 v[4:5], s[30:31]
	s_addc_u32 s85, s1, 0
	v_mad_i64_i32 v[6:7], s[0:1], v6, s36, v[4:5]
	v_writelane_b32 v255, s45, 4
	s_mov_b32 s1, s27
	v_writelane_b32 v255, s0, 5
	v_or_b32_e32 v8, s5, v14
	s_mov_b32 s81, s27
	v_writelane_b32 v255, s1, 6
	v_mad_i64_i32 v[4:5], s[0:1], v8, s36, v[4:5]
	s_add_u32 s9, s12, s80
	v_ashrrev_i32_e32 v13, 3, v15
	v_ashrrev_i32_e32 v17, 4, v15
	v_lshl_add_u64 v[6:7], v[6:7], 0, s[80:81]
	v_lshl_add_u64 v[4:5], v[4:5], 0, s[80:81]
	s_addc_u32 s81, s13, 0
	v_add_u32_e32 v16, s34, v13
	v_xor_b32_e32 v13, v13, v15
	v_lshlrev_b32_e32 v8, 3, v17
	s_add_u32 s4, s9, 0x400
	v_mul_lo_u32 v16, v16, s37
	v_lshlrev_b32_e32 v13, 3, v13
	v_writelane_b32 v255, s5, 7
	v_ashrrev_i32_e32 v9, 31, v8
	s_addc_u32 s5, s81, 0
	v_and_or_b32 v13, v13, 56, v16
	v_lshlrev_b64 v[8:9], 1, v[8:9]
	s_add_u32 s0, s71, 0x800
	v_lshlrev_b32_e32 v180, 1, v13
	v_add_u32_e32 v13, s35, v17
	v_lshl_add_u64 v[6:7], v[6:7], 0, v[8:9]
	v_lshl_add_u64 v[4:5], v[4:5], 0, v[8:9]
	s_addc_u32 s1, s94, 0
	v_lshlrev_b32_e32 v16, 1, v13
	global_load_dwordx4 v[32:35], v[6:7], off nt
	global_load_dwordx4 v[8:11], v[4:5], off nt
	global_load_dwordx4 v[28:31], v[6:7], off offset:64 nt
	s_nop 0
	global_load_dwordx4 v[4:7], v[4:5], off offset:64 nt
	v_xor_b32_e32 v16, v16, v15
	v_and_b32_e32 v18, 1, v15
	s_waitcnt lgkmcnt(0)
	s_barrier
	s_add_u32 s6, s0, 0x70000
	v_and_or_b32 v16, v16, 14, v18
	v_mul_lo_u32 v13, v13, s36
	s_addc_u32 s7, s1, 0
	s_mov_b32 m0, s90
	v_lshl_or_b32 v184, v16, 4, v13
	global_load_lds_dwordx4 v180, s[4:5]
	s_mov_b32 m0, s43
	v_lshlrev_b32_e32 v16, 2, v17
	global_load_lds_dwordx4 v184, s[0:1]
	s_add_u32 s0, s9, 0xe0400
	s_addc_u32 s1, s81, 0
	s_add_u32 s4, s71, 0xe0800
	v_bfe_u32 v13, v15, 2, 2
	v_lshlrev_b32_e32 v19, 3, v15
	s_mov_b32 m0, s38
	s_addc_u32 s5, s94, 0
	v_or_b32_e32 v18, v16, v13
	v_and_b32_e32 v19, 24, v19
	global_load_lds_dwordx4 v184, s[6:7]
	s_add_u32 s6, s4, 0x70000
	v_lshlrev_b32_e32 v13, 5, v18
	v_lshl_or_b32 v18, v18, 8, v19
	v_bitop3_b32 v19, v17, v15, 7 bitop3:0x78
	v_add_u32_e32 v17, 4, v17
	s_addc_u32 s7, s5, 0
	s_add_i32 s8, s8, s29
	v_bitop3_b32 v15, v17, v15, 7 bitop3:0x78
	v_add_u32_e32 v188, 0x4000, v18
	v_or_b32_e32 v18, s8, v14
	v_lshlrev_b32_e32 v205, 4, v15
	v_lshl_add_u32 v15, s83, 6, v16
	v_cvt_f32_u32_e32 v18, v18
	v_cvt_f32_i32_e32 v17, v15
	s_mov_b32 m0, s39
	v_writelane_b32 v255, s9, 8
	v_sub_f32_e32 v17, v17, v18
	global_load_lds_dwordx4 v180, s[0:1]
	v_cmp_lt_f32_e64 s[0:1], 0, v17
	v_mul_f32_e32 v17, v17, v12
	v_exp_f32_e32 v189, v17
	v_or_b32_e32 v17, 1, v15
	v_cvt_f32_i32_e32 v17, v17
	s_mov_b32 m0, s40
	s_add_i32 s14, s14, s29
	global_load_lds_dwordx4 v184, s[4:5]
	v_sub_f32_e32 v17, v17, v18
	v_cmp_lt_f32_e64 s[68:69], 0, v17
	v_mul_f32_e32 v17, v17, v12
	v_exp_f32_e32 v190, v17
	v_or_b32_e32 v17, 2, v15
	v_cvt_f32_i32_e32 v17, v17
	s_mov_b32 m0, s41
	v_lshlrev_b32_e32 v201, 7, v14
	global_load_lds_dwordx4 v184, s[6:7]
	v_sub_f32_e32 v17, v17, v18
	v_cmp_lt_f32_e64 s[4:5], 0, v17
	v_mul_f32_e32 v17, v17, v12
	v_exp_f32_e32 v191, v17
	v_or_b32_e32 v17, 3, v15
	v_cvt_f32_i32_e32 v17, v17
	v_or_b32_e32 v14, s14, v14
	v_cvt_f32_u32_e32 v14, v14
	v_sub_f32_e32 v17, v17, v18
	v_cmp_lt_f32_e64 s[6:7], 0, v17
	v_mul_f32_e32 v17, v17, v12
	v_exp_f32_e32 v192, v17
	v_add_u32_e32 v17, 16, v15
	v_cvt_f32_i32_e32 v17, v17
	v_mov_b32_e32 v48, v181
	v_mov_b32_e32 v49, v181
	v_mov_b32_e32 v50, v181
	v_sub_f32_e32 v17, v17, v18
	v_cmp_lt_f32_e64 s[8:9], 0, v17
	v_mul_f32_e32 v17, v17, v12
	v_exp_f32_e32 v193, v17
	v_add_u32_e32 v17, 17, v15
	v_cvt_f32_i32_e32 v17, v17
	v_mov_b32_e32 v51, v181
	v_and_b32_e32 v187, 0xe0, v13
	v_lshlrev_b32_e32 v204, 4, v19
	v_sub_f32_e32 v17, v17, v18
	v_cmp_lt_f32_e64 s[10:11], 0, v17
	v_mul_f32_e32 v17, v17, v12
	v_exp_f32_e32 v194, v17
	v_add_u32_e32 v17, 18, v15
	v_cvt_f32_i32_e32 v17, v17
	v_bitop3_b32 v207, v13, 32, v186 bitop3:0x6c
	v_bitop3_b32 v226, v13, 64, v186 bitop3:0x6c
	v_bitop3_b32 v224, v13, s73, v186 bitop3:0x6c
	v_sub_f32_e32 v17, v17, v18
	v_cmp_lt_f32_e64 s[12:13], 0, v17
	v_mul_f32_e32 v17, v17, v12
	v_exp_f32_e32 v195, v17
	v_add_u32_e32 v17, 19, v15
	v_cvt_f32_i32_e32 v17, v17
	v_bitop3_b32 v221, v13, s74, v186 bitop3:0x6c
	v_bitop3_b32 v220, v13, s75, v186 bitop3:0x6c
	v_bitop3_b32 v217, v13, s79, v186 bitop3:0x6c
	v_sub_f32_e32 v17, v17, v18
	v_cmp_lt_f32_e64 s[14:15], 0, v17
	v_mul_f32_e32 v17, v17, v12
	v_exp_f32_e32 v196, v17
	v_add_u32_e32 v17, 32, v15
	v_cvt_f32_i32_e32 v17, v17
	v_bitop3_b32 v216, v13, s67, v13 bitop3:0xc
	v_mov_b64_e32 v[44:45], v[48:49]
; __device__ __forceinline__ void ret_pair(LAS unsigned char* lds, const bf16_t* Z, bf16_t* MIX, int b, int h, int tA, int tB, const float* gain, int wid) {
;     ...
;     f32x4 OA[8], OB[8];
; #pragma unroll
;     for (int eb = 0; eb < 8; ++eb) { OA[eb] = (f32x4){0.f, 0.f, 0.f, 0.f}; OB[eb] = OA[eb]; }
;     const char* kbase = (const char*)(Z + (size_t)(b * SEQ) * DIN + kcol);
;     const char* vbase = (const char*)(Z + (size_t)(b * SEQ) * DIN + vcol);
;     const unsigned krow = (unsigned)(8 * wid + (lane >> 3));
;     const unsigned kso = (krow * DIN + 8u * ((unsigned)(lane & 7) ^ (krow & 7u))) * 2u;
;     const unsigned vrow = (unsigned)(4 * wid + (lane >> 4));
;     const unsigned vso = (vrow * DIN + 8u * (2u * ((((unsigned)lane & 15u) >> 1) ^ (vrow & 7u)) + ((unsigned)lane & 1u))) * 2u;
;     constexpr int RING = 32768;
;     ...
;     asm volatile("s_waitcnt lgkmcnt(0)\n\ts_barrier" ::: "memory");
;     RP_DMA(0, 0); RP_DMA(1, 1);
;     asm volatile("s_waitcnt vmcnt(3) lgkmcnt(0)\n\ts_barrier" ::: "memory");
;     const unsigned kfo = (unsigned)(q16 * 128), ksw = (unsigned)(q16 & 7);
;     const unsigned vrr = (unsigned)(4 * quad + (q16 >> 2)), vx32 = (vrr & 7u) * 32u, vb0 = 16384u + vrr * 256u + 8u * (unsigned)(q16 & 3);
;     const float iqA = (float)(128 * tA + 16 * wid + q16), iqB = (float)(128 * tB + 16 * wid + q16);
	v_mov_b64_e32 v[40:41], v[48:49]
	v_sub_f32_e32 v17, v17, v18
	v_cmp_lt_f32_e64 s[16:17], 0, v17
	v_mul_f32_e32 v17, v17, v12
	v_exp_f32_e32 v197, v17
	v_add_u32_e32 v17, 33, v15
	v_cvt_f32_i32_e32 v17, v17
	v_mov_b64_e32 v[36:37], v[48:49]
	v_mov_b64_e32 v[24:25], v[48:49]
	v_mov_b64_e32 v[20:21], v[48:49]
	v_sub_f32_e32 v17, v17, v18
	v_cmp_lt_f32_e64 s[18:19], 0, v17
	v_mul_f32_e32 v17, v17, v12
	v_exp_f32_e32 v198, v17
	v_add_u32_e32 v17, 34, v15
	v_cvt_f32_i32_e32 v17, v17
	v_mov_b64_e32 v[82:83], v[50:51]
	v_mov_b64_e32 v[78:79], v[50:51]
	v_mov_b64_e32 v[74:75], v[50:51]
	v_sub_f32_e32 v17, v17, v18
	v_cmp_lt_f32_e64 s[20:21], 0, v17
	v_mul_f32_e32 v17, v17, v12
	v_exp_f32_e32 v199, v17
	v_add_u32_e32 v17, 35, v15
	v_cvt_f32_i32_e32 v17, v17
	v_mov_b64_e32 v[70:71], v[50:51]
	v_mov_b64_e32 v[66:67], v[50:51]
	v_mov_b64_e32 v[62:63], v[50:51]
	v_sub_f32_e32 v17, v17, v18
	v_cmp_lt_f32_e64 s[22:23], 0, v17
	v_mul_f32_e32 v17, v17, v12
	v_exp_f32_e32 v200, v17
	v_add_u32_e32 v17, 48, v15
	v_cvt_f32_i32_e32 v17, v17
	v_mov_b64_e32 v[58:59], v[50:51]
	v_mov_b64_e32 v[54:55], v[50:51]
	v_mov_b32_e32 v185, v181
	v_sub_f32_e32 v17, v17, v18
	v_cmp_lt_f32_e64 s[24:25], 0, v17
	v_mul_f32_e32 v17, v17, v12
	v_exp_f32_e32 v203, v17
	v_add_u32_e32 v17, 49, v15
	v_cvt_f32_i32_e32 v17, v17
	s_mov_b32 s66, 0
	v_mov_b64_e32 v[46:47], v[50:51]
	v_mov_b64_e32 v[42:43], v[50:51]
	v_sub_f32_e32 v17, v17, v18
	v_cmp_lt_f32_e64 s[26:27], 0, v17
	v_mul_f32_e32 v17, v17, v12
	v_exp_f32_e32 v206, v17
	v_add_u32_e32 v17, 50, v15
	v_add_u32_e32 v15, 51, v15
	v_cvt_f32_i32_e32 v15, v15
	v_cvt_f32_i32_e32 v17, v17
	v_mov_b64_e32 v[38:39], v[50:51]
	v_mov_b64_e32 v[26:27], v[50:51]
	v_sub_f32_e32 v15, v15, v18
	v_cmp_lt_f32_e64 s[34:35], 0, v15
	v_mul_f32_e32 v15, v15, v12
	v_exp_f32_e32 v211, v15
	v_lshl_add_u32 v15, s91, 6, v16
	v_cvt_f32_i32_e32 v16, v15
	v_sub_f32_e32 v17, v17, v18
	v_cmp_lt_f32_e64 s[28:29], 0, v17
	v_mul_f32_e32 v17, v17, v12
	v_sub_f32_e32 v16, v16, v14
	v_cmp_lt_f32_e64 s[30:31], 0, v16
	v_mul_f32_e32 v16, v16, v12
	v_exp_f32_e32 v208, v16
	v_or_b32_e32 v16, 1, v15
	v_cvt_f32_i32_e32 v16, v16
	v_exp_f32_e32 v209, v17
	v_mov_b64_e32 v[22:23], v[50:51]
	v_mov_b64_e32 v[80:81], v[48:49]
	v_sub_f32_e32 v16, v16, v14
	v_cmp_lt_f32_e64 s[36:37], 0, v16
	v_mul_f32_e32 v16, v16, v12
	v_exp_f32_e32 v210, v16
	v_or_b32_e32 v16, 2, v15
	v_cvt_f32_i32_e32 v16, v16
	v_mov_b64_e32 v[76:77], v[48:49]
	v_mov_b64_e32 v[72:73], v[48:49]
	v_mov_b64_e32 v[68:69], v[48:49]
	v_sub_f32_e32 v16, v16, v14
	v_cmp_lt_f32_e64 s[38:39], 0, v16
	v_mul_f32_e32 v16, v16, v12
	v_exp_f32_e32 v252, v16
	v_or_b32_e32 v16, 3, v15
	v_cvt_f32_i32_e32 v16, v16
	v_mov_b64_e32 v[64:65], v[48:49]
	v_mov_b64_e32 v[60:61], v[48:49]
	v_mov_b64_e32 v[56:57], v[48:49]
	v_sub_f32_e32 v16, v16, v14
	v_cmp_lt_f32_e64 s[40:41], 0, v16
	v_mul_f32_e32 v16, v16, v12
	v_exp_f32_e32 v253, v16
	v_add_u32_e32 v16, 16, v15
	v_cvt_f32_i32_e32 v16, v16
	v_mov_b64_e32 v[52:53], v[48:49]
	s_mov_b32 s73, 0
	v_sub_f32_e32 v16, v16, v14
	v_cmp_lt_f32_e64 s[42:43], 0, v16
	v_mul_f32_e32 v16, v16, v12
	v_exp_f32_e32 v202, v16
	v_add_u32_e32 v16, 17, v15
	v_cvt_f32_i32_e32 v16, v16
	v_sub_f32_e32 v16, v16, v14
	v_cmp_lt_f32_e64 s[44:45], 0, v16
	v_mul_f32_e32 v16, v16, v12
	v_exp_f32_e32 v182, v16
	v_add_u32_e32 v16, 18, v15
	v_cvt_f32_i32_e32 v16, v16
	v_sub_f32_e32 v16, v16, v14
	v_cmp_lt_f32_e64 s[46:47], 0, v16
	v_mul_f32_e32 v16, v16, v12
	v_exp_f32_e32 v218, v16
	v_add_u32_e32 v16, 19, v15
	v_cvt_f32_i32_e32 v16, v16
	v_sub_f32_e32 v16, v16, v14
	v_cmp_lt_f32_e64 s[48:49], 0, v16
	v_mul_f32_e32 v16, v16, v12
	v_exp_f32_e32 v219, v16
	v_add_u32_e32 v16, 32, v15
	v_cvt_f32_i32_e32 v16, v16
	v_sub_f32_e32 v16, v16, v14
	v_cmp_lt_f32_e64 s[50:51], 0, v16
	v_mul_f32_e32 v16, v16, v12
	v_exp_f32_e32 v222, v16
	v_add_u32_e32 v16, 33, v15
	v_cvt_f32_i32_e32 v16, v16
	v_sub_f32_e32 v16, v16, v14
	v_cmp_lt_f32_e64 s[52:53], 0, v16
	v_mul_f32_e32 v16, v16, v12
	v_exp_f32_e32 v223, v16
	v_add_u32_e32 v16, 34, v15
	v_cvt_f32_i32_e32 v16, v16
	v_sub_f32_e32 v16, v16, v14
	v_cmp_lt_f32_e64 s[54:55], 0, v16
	v_mul_f32_e32 v16, v16, v12
	v_exp_f32_e32 v225, v16
	v_add_u32_e32 v16, 35, v15
	v_cvt_f32_i32_e32 v16, v16
	v_sub_f32_e32 v16, v16, v14
	v_cmp_lt_f32_e64 s[56:57], 0, v16
	v_mul_f32_e32 v16, v16, v12
	v_exp_f32_e32 v227, v16
	v_add_u32_e32 v16, 48, v15
	v_cvt_f32_i32_e32 v16, v16
	v_sub_f32_e32 v16, v16, v14
	v_cmp_lt_f32_e64 s[58:59], 0, v16
	v_mul_f32_e32 v16, v16, v12
	v_exp_f32_e32 v228, v16
	v_add_u32_e32 v16, 49, v15
	v_cvt_f32_i32_e32 v16, v16
	v_sub_f32_e32 v16, v16, v14
	v_cmp_lt_f32_e64 s[60:61], 0, v16
	v_mul_f32_e32 v16, v16, v12
	v_exp_f32_e32 v229, v16
	v_add_u32_e32 v16, 50, v15
	v_add_u32_e32 v15, 51, v15
	v_cvt_f32_i32_e32 v16, v16
	v_cvt_f32_i32_e32 v15, v15
	v_sub_f32_e32 v16, v16, v14
	v_sub_f32_e32 v14, v15, v14
	v_cmp_lt_f32_e64 s[62:63], 0, v16
	v_mul_f32_e32 v16, v16, v12
	v_mul_f32_e32 v12, v14, v12
	v_exp_f32_e32 v230, v16
	v_exp_f32_e32 v231, v12
	v_cmp_lt_f32_e64 s[64:65], 0, v14
	v_mov_b64_e32 v[16:17], v[48:49]
	v_mov_b64_e32 v[12:13], v[48:49]
	v_mov_b64_e32 v[18:19], v[50:51]
	v_mov_b64_e32 v[14:15], v[50:51]
	s_waitcnt vmcnt(3) lgkmcnt(0)
	s_barrier
	s_mov_b32 s98, 0
	s_and_b32 s72, s98, 3
	s_lshl_b32 s72, s72, 15
	s_add_i32 s73, s98, 3
	s_and_b32 s73, s73, 3
	s_lshl_b32 s73, s73, 15
	s_add_i32 s74, s98, 2
	s_and_b32 s74, s74, 3
	s_lshl_b32 s74, s74, 15
	s_add_i32 s74, s74, s90
	v_add_u32_e32 v212, s72, v201
	v_add_u32_e32 v213, v212, v204
	v_add_u32_e32 v214, v212, v205
	ds_read_b128 v[84:87], v213
	ds_read_b128 v[88:91], v213 offset:2048
	ds_read_b128 v[92:95], v214
	ds_read_b128 v[96:99], v214 offset:2048
	ds_read_b128 v[100:103], v213 offset:4096
	ds_read_b128 v[104:107], v213 offset:6144
	ds_read_b128 v[108:111], v214 offset:4096
	ds_read_b128 v[112:115], v214 offset:6144
	s_cmp_ge_u32 s98, s70
	s_cbranch_scc1 .Lrx_ndf
	s_add_u32 s78, s2, 0x70000
	s_addc_u32 s79, s3, 0
	s_mov_b32 m0, s74
	s_nop 0
	global_load_lds_dwordx4 v180, s[84:85]
	s_add_i32 m0, s74, 0x4000
	s_nop 0
	global_load_lds_dwordx4 v184, s[2:3]
	s_add_i32 m0, s74, 0x6000
	s_nop 0
	global_load_lds_dwordx4 v184, s[78:79]
	s_add_u32 s2, s2, 0xe0000
	s_addc_u32 s3, s3, 0
	s_add_u32 s84, s84, 0xe0000
	s_addc_u32 s85, s85, 0
